# per-slice block barrier in PEER passes keeps all waves of a block in the same L2-resident table slice
# speedup vs baseline: 1.1736x; 1.0028x over previous
; DEV void phase_peer_expert(const Params& p, int layer, int M, bool final_, int part, char* smem) {
;     ...
; #pragma unroll 2
;     for (int st = 0; st < 16; st++) {
;       if (st + 1 < 16) {
;         const unsigned char* r0p = U + (size_t)se[(st + 1) * 8 + g] * 1024 + l16 * 16;
;         const unsigned char* r1p = U + (size_t)se[(st + 1) * 8 + 4 + g] * 1024 + l16 * 16;
; #pragma unroll
;         for (int c = 0; c < 4; c++) { nxt[c] = *(const u32x4*)(r0p + c * 256); nxt[4 + c] = *(const u32x4*)(r1p + c * 256); }
;       }
;       f32x2 da = (f32x2){0.f, 0.f}, db = (f32x2){0.f, 0.f};
; #pragma unroll
;       for (int c = 0; c < 4; c++) {
;         da = fp8dot4(cur[c][0], xf[c * 8 + 0], xf[c * 8 + 1], da); da = fp8dot4(cur[c][1], xf[c * 8 + 2], xf[c * 8 + 3], da);
;         da = fp8dot4(cur[c][2], xf[c * 8 + 4], xf[c * 8 + 5], da); da = fp8dot4(cur[c][3], xf[c * 8 + 6], xf[c * 8 + 7], da);
;         db = fp8dot4(cur[4 + c][0], xf[c * 8 + 0], xf[c * 8 + 1], db); db = fp8dot4(cur[4 + c][1], xf[c * 8 + 2], xf[c * 8 + 3], db);
;         db = fp8dot4(cur[4 + c][2], xf[c * 8 + 4], xf[c * 8 + 5], db); db = fp8dot4(cur[4 + c][3], xf[c * 8 + 6], xf[c * 8 + 7], db);
;       }
;       float d0 = da.x + da.y, d1 = db.x + db.y;
;       d0 += __shfl_xor(d0, 1); d1 += __shfl_xor(d1, 1);
;       d0 += __shfl_xor(d0, 2); d1 += __shfl_xor(d1, 2);
;       d0 += __shfl_xor(d0, 4); d1 += __shfl_xor(d1, 4);
;       d0 += __shfl_xor(d0, 8); d1 += __shfl_xor(d1, 8);
;       const int s0 = st * 8 + g, s1 = s0 + 4;
;       d0 *= su[s0]; d1 *= su[s1];
;       const float a0 = 0.5f * d0 * (1.f + erff(d0 * 0.70710678118f));
;       const float a1 = 0.5f * d1 * (1.f + erff(d1 * 0.70710678118f));
;       if (l16 == 0) { COEF[(size_t)m * 128 + s0] = sg[s0] * a0; COEF[(size_t)m * 128 + s1] = sg[s1] * a1; }
.Lu_loop:
	v_add_u32_e32 v159, s29, v158
	global_load_dwordx4 v[82:85], v159, s[12:13]
	global_load_dwordx4 v[86:89], v159, s[12:13] offset:16
	v_add_u32_e32 v160, s32, v157
	ds_read_b128 v[66:69], v160 offset:0
	ds_read_b128 v[70:73], v160 offset:16
	ds_read_b128 v[74:77], v160 offset:32
	ds_read_b128 v[78:81], v160 offset:48
	v_mov_b32_e32 v146, 0
	v_mov_b32_e32 v147, 0
	s_waitcnt vmcnt(10)
	v_cvt_pk_f32_fp8_e32 v[122:123], v2
	v_cvt_pk_f32_fp8_e32 v[126:127], v6
	v_cvt_pk_f32_fp8_sdwa v[124:125], v2 src0_sel:WORD_1
	v_cvt_pk_f32_fp8_sdwa v[128:129], v6 src0_sel:WORD_1
	v_pk_fma_f32 v[106:107], v[122:123], v[90:91], 0 op_sel_hi:[1,1,0]
	v_pk_fma_f32 v[108:109], v[126:127], v[90:91], 0 op_sel_hi:[1,1,0]
	v_pk_fma_f32 v[106:107], v[124:125], v[92:93], v[106:107]
	v_pk_fma_f32 v[108:109], v[128:129], v[92:93], v[108:109]
	v_cvt_pk_f32_fp8_e32 v[122:123], v3
	v_cvt_pk_f32_fp8_e32 v[126:127], v7
	v_cvt_pk_f32_fp8_sdwa v[124:125], v3 src0_sel:WORD_1
	v_cvt_pk_f32_fp8_sdwa v[128:129], v7 src0_sel:WORD_1
	v_pk_fma_f32 v[106:107], v[122:123], v[94:95], v[106:107]
	v_pk_fma_f32 v[108:109], v[126:127], v[94:95], v[108:109]
	v_pk_fma_f32 v[106:107], v[124:125], v[96:97], v[106:107]
	v_pk_fma_f32 v[108:109], v[128:129], v[96:97], v[108:109]
	v_cvt_pk_f32_fp8_e32 v[122:123], v4
	v_cvt_pk_f32_fp8_e32 v[126:127], v8
	v_cvt_pk_f32_fp8_sdwa v[124:125], v4 src0_sel:WORD_1
	v_cvt_pk_f32_fp8_sdwa v[128:129], v8 src0_sel:WORD_1
	v_pk_fma_f32 v[106:107], v[122:123], v[98:99], v[106:107]
	v_pk_fma_f32 v[108:109], v[126:127], v[98:99], v[108:109]
	v_pk_fma_f32 v[106:107], v[124:125], v[100:101], v[106:107]
	v_pk_fma_f32 v[108:109], v[128:129], v[100:101], v[108:109]
	v_cvt_pk_f32_fp8_e32 v[122:123], v5
	v_cvt_pk_f32_fp8_e32 v[126:127], v9
	v_cvt_pk_f32_fp8_sdwa v[124:125], v5 src0_sel:WORD_1
	v_cvt_pk_f32_fp8_sdwa v[128:129], v9 src0_sel:WORD_1
	v_pk_fma_f32 v[106:107], v[122:123], v[102:103], v[106:107]
	v_pk_fma_f32 v[108:109], v[126:127], v[102:103], v[108:109]
	v_pk_fma_f32 v[106:107], v[124:125], v[104:105], v[106:107]
	v_pk_fma_f32 v[108:109], v[128:129], v[104:105], v[108:109]
	v_cvt_pk_f32_fp8_e32 v[122:123], v10
	v_cvt_pk_f32_fp8_e32 v[126:127], v14
	v_cvt_pk_f32_fp8_sdwa v[124:125], v10 src0_sel:WORD_1
	v_cvt_pk_f32_fp8_sdwa v[128:129], v14 src0_sel:WORD_1
	v_pk_fma_f32 v[110:111], v[122:123], v[90:91], 0 op_sel_hi:[1,1,0]
	v_pk_fma_f32 v[112:113], v[126:127], v[90:91], 0 op_sel_hi:[1,1,0]
	v_pk_fma_f32 v[110:111], v[124:125], v[92:93], v[110:111]
	v_pk_fma_f32 v[112:113], v[128:129], v[92:93], v[112:113]
	v_cvt_pk_f32_fp8_e32 v[122:123], v11
	v_cvt_pk_f32_fp8_e32 v[126:127], v15
	v_cvt_pk_f32_fp8_sdwa v[124:125], v11 src0_sel:WORD_1
	v_cvt_pk_f32_fp8_sdwa v[128:129], v15 src0_sel:WORD_1
	v_pk_fma_f32 v[110:111], v[122:123], v[94:95], v[110:111]
	v_pk_fma_f32 v[112:113], v[126:127], v[94:95], v[112:113]
	v_pk_fma_f32 v[110:111], v[124:125], v[96:97], v[110:111]
	v_pk_fma_f32 v[112:113], v[128:129], v[96:97], v[112:113]
	v_cvt_pk_f32_fp8_e32 v[122:123], v12
	v_cvt_pk_f32_fp8_e32 v[126:127], v16
	v_cvt_pk_f32_fp8_sdwa v[124:125], v12 src0_sel:WORD_1
	v_cvt_pk_f32_fp8_sdwa v[128:129], v16 src0_sel:WORD_1
	v_pk_fma_f32 v[110:111], v[122:123], v[98:99], v[110:111]
	v_pk_fma_f32 v[112:113], v[126:127], v[98:99], v[112:113]
	v_pk_fma_f32 v[110:111], v[124:125], v[100:101], v[110:111]
	v_pk_fma_f32 v[112:113], v[128:129], v[100:101], v[112:113]
	v_cvt_pk_f32_fp8_e32 v[122:123], v13
	v_cvt_pk_f32_fp8_e32 v[126:127], v17
	v_cvt_pk_f32_fp8_sdwa v[124:125], v13 src0_sel:WORD_1
	v_cvt_pk_f32_fp8_sdwa v[128:129], v17 src0_sel:WORD_1
	v_pk_fma_f32 v[110:111], v[122:123], v[102:103], v[110:111]
	v_pk_fma_f32 v[112:113], v[126:127], v[102:103], v[112:113]
	v_pk_fma_f32 v[110:111], v[124:125], v[104:105], v[110:111]
	v_pk_fma_f32 v[112:113], v[128:129], v[104:105], v[112:113]
	v_cvt_pk_f32_fp8_e32 v[122:123], v18
	v_cvt_pk_f32_fp8_e32 v[126:127], v22
	v_cvt_pk_f32_fp8_sdwa v[124:125], v18 src0_sel:WORD_1
	v_cvt_pk_f32_fp8_sdwa v[128:129], v22 src0_sel:WORD_1
	v_pk_fma_f32 v[114:115], v[122:123], v[90:91], 0 op_sel_hi:[1,1,0]
	v_pk_fma_f32 v[116:117], v[126:127], v[90:91], 0 op_sel_hi:[1,1,0]
	v_pk_fma_f32 v[114:115], v[124:125], v[92:93], v[114:115]
	v_pk_fma_f32 v[116:117], v[128:129], v[92:93], v[116:117]
	v_cvt_pk_f32_fp8_e32 v[122:123], v19
	v_cvt_pk_f32_fp8_e32 v[126:127], v23
	v_cvt_pk_f32_fp8_sdwa v[124:125], v19 src0_sel:WORD_1
	v_cvt_pk_f32_fp8_sdwa v[128:129], v23 src0_sel:WORD_1
	v_pk_fma_f32 v[114:115], v[122:123], v[94:95], v[114:115]
	v_pk_fma_f32 v[116:117], v[126:127], v[94:95], v[116:117]
	v_pk_fma_f32 v[114:115], v[124:125], v[96:97], v[114:115]
	v_pk_fma_f32 v[116:117], v[128:129], v[96:97], v[116:117]
	v_cvt_pk_f32_fp8_e32 v[122:123], v20
	v_cvt_pk_f32_fp8_e32 v[126:127], v24
	v_cvt_pk_f32_fp8_sdwa v[124:125], v20 src0_sel:WORD_1
	v_cvt_pk_f32_fp8_sdwa v[128:129], v24 src0_sel:WORD_1
	v_pk_fma_f32 v[114:115], v[122:123], v[98:99], v[114:115]
	v_pk_fma_f32 v[116:117], v[126:127], v[98:99], v[116:117]
	v_pk_fma_f32 v[114:115], v[124:125], v[100:101], v[114:115]
	v_pk_fma_f32 v[116:117], v[128:129], v[100:101], v[116:117]
	v_cvt_pk_f32_fp8_e32 v[122:123], v21
	v_cvt_pk_f32_fp8_e32 v[126:127], v25
	v_cvt_pk_f32_fp8_sdwa v[124:125], v21 src0_sel:WORD_1
	v_cvt_pk_f32_fp8_sdwa v[128:129], v25 src0_sel:WORD_1
	v_pk_fma_f32 v[114:115], v[122:123], v[102:103], v[114:115]
	v_pk_fma_f32 v[116:117], v[126:127], v[102:103], v[116:117]
	v_pk_fma_f32 v[114:115], v[124:125], v[104:105], v[114:115]
	v_pk_fma_f32 v[116:117], v[128:129], v[104:105], v[116:117]
	v_cvt_pk_f32_fp8_e32 v[122:123], v26
	v_cvt_pk_f32_fp8_e32 v[126:127], v30
	v_cvt_pk_f32_fp8_sdwa v[124:125], v26 src0_sel:WORD_1
; DEV void phase_peer_expert(const Params& p, int layer, int M, bool final_, int part, char* smem) {
;     ...
;       f32x2 da = (f32x2){0.f, 0.f}, db = (f32x2){0.f, 0.f};
; #pragma unroll
;       for (int c = 0; c < 4; c++) {
;         da = fp8dot4(cur[c][0], xf[c * 8 + 0], xf[c * 8 + 1], da); da = fp8dot4(cur[c][1], xf[c * 8 + 2], xf[c * 8 + 3], da);
;         da = fp8dot4(cur[c][2], xf[c * 8 + 4], xf[c * 8 + 5], da); da = fp8dot4(cur[c][3], xf[c * 8 + 6], xf[c * 8 + 7], da);
;         db = fp8dot4(cur[4 + c][0], xf[c * 8 + 0], xf[c * 8 + 1], db); db = fp8dot4(cur[4 + c][1], xf[c * 8 + 2], xf[c * 8 + 3], db);
;         db = fp8dot4(cur[4 + c][2], xf[c * 8 + 4], xf[c * 8 + 5], db); db = fp8dot4(cur[4 + c][3], xf[c * 8 + 6], xf[c * 8 + 7], db);
;       }
;       float d0 = da.x + da.y, d1 = db.x + db.y;
;       d0 += __shfl_xor(d0, 1); d1 += __shfl_xor(d1, 1);
;       d0 += __shfl_xor(d0, 2); d1 += __shfl_xor(d1, 2);
;       d0 += __shfl_xor(d0, 4); d1 += __shfl_xor(d1, 4);
;       d0 += __shfl_xor(d0, 8); d1 += __shfl_xor(d1, 8);
;       const int s0 = st * 8 + g, s1 = s0 + 4;
;       d0 *= su[s0]; d1 *= su[s1];
;       const float a0 = 0.5f * d0 * (1.f + erff(d0 * 0.70710678118f));
;       const float a1 = 0.5f * d1 * (1.f + erff(d1 * 0.70710678118f));
;       if (l16 == 0) { COEF[(size_t)m * 128 + s0] = sg[s0] * a0; COEF[(size_t)m * 128 + s1] = sg[s1] * a1; }
	v_cvt_pk_f32_fp8_sdwa v[128:129], v30 src0_sel:WORD_1
	v_pk_fma_f32 v[118:119], v[122:123], v[90:91], 0 op_sel_hi:[1,1,0]
	v_pk_fma_f32 v[120:121], v[126:127], v[90:91], 0 op_sel_hi:[1,1,0]
	v_pk_fma_f32 v[118:119], v[124:125], v[92:93], v[118:119]
	v_pk_fma_f32 v[120:121], v[128:129], v[92:93], v[120:121]
	v_cvt_pk_f32_fp8_e32 v[122:123], v27
	v_cvt_pk_f32_fp8_e32 v[126:127], v31
	v_cvt_pk_f32_fp8_sdwa v[124:125], v27 src0_sel:WORD_1
	v_cvt_pk_f32_fp8_sdwa v[128:129], v31 src0_sel:WORD_1
	v_pk_fma_f32 v[118:119], v[122:123], v[94:95], v[118:119]
	v_pk_fma_f32 v[120:121], v[126:127], v[94:95], v[120:121]
	v_pk_fma_f32 v[118:119], v[124:125], v[96:97], v[118:119]
	v_pk_fma_f32 v[120:121], v[128:129], v[96:97], v[120:121]
	v_cvt_pk_f32_fp8_e32 v[122:123], v28
	v_cvt_pk_f32_fp8_e32 v[126:127], v32
	v_cvt_pk_f32_fp8_sdwa v[124:125], v28 src0_sel:WORD_1
	v_cvt_pk_f32_fp8_sdwa v[128:129], v32 src0_sel:WORD_1
	v_pk_fma_f32 v[118:119], v[122:123], v[98:99], v[118:119]
	v_pk_fma_f32 v[120:121], v[126:127], v[98:99], v[120:121]
	v_pk_fma_f32 v[118:119], v[124:125], v[100:101], v[118:119]
	v_pk_fma_f32 v[120:121], v[128:129], v[100:101], v[120:121]
	v_cvt_pk_f32_fp8_e32 v[122:123], v29
	v_cvt_pk_f32_fp8_e32 v[126:127], v33
	v_cvt_pk_f32_fp8_sdwa v[124:125], v29 src0_sel:WORD_1
	v_cvt_pk_f32_fp8_sdwa v[128:129], v33 src0_sel:WORD_1
	v_pk_fma_f32 v[118:119], v[122:123], v[102:103], v[118:119]
	v_pk_fma_f32 v[120:121], v[126:127], v[102:103], v[120:121]
	v_pk_fma_f32 v[118:119], v[124:125], v[104:105], v[118:119]
	v_pk_fma_f32 v[120:121], v[128:129], v[104:105], v[120:121]
	s_nop 0
	v_add_f32_e32 v138, v106, v107
	v_add_f32_e32 v139, v108, v109
	v_add_f32_e32 v140, v110, v111
	v_add_f32_e32 v141, v112, v113
	v_add_f32_e32 v142, v114, v115
	v_add_f32_e32 v143, v116, v117
	v_add_f32_e32 v144, v118, v119
	v_add_f32_e32 v145, v120, v121
	s_nop 1
	v_add_f32_dpp v138, v138, v138 quad_perm:[1,0,3,2] row_mask:0xf bank_mask:0xf
	v_add_f32_dpp v139, v139, v139 quad_perm:[1,0,3,2] row_mask:0xf bank_mask:0xf
	v_add_f32_dpp v140, v140, v140 quad_perm:[1,0,3,2] row_mask:0xf bank_mask:0xf
	v_add_f32_dpp v141, v141, v141 quad_perm:[1,0,3,2] row_mask:0xf bank_mask:0xf
	v_add_f32_dpp v142, v142, v142 quad_perm:[1,0,3,2] row_mask:0xf bank_mask:0xf
	v_add_f32_dpp v143, v143, v143 quad_perm:[1,0,3,2] row_mask:0xf bank_mask:0xf
	v_add_f32_dpp v144, v144, v144 quad_perm:[1,0,3,2] row_mask:0xf bank_mask:0xf
	v_add_f32_dpp v145, v145, v145 quad_perm:[1,0,3,2] row_mask:0xf bank_mask:0xf
	v_add_f32_dpp v138, v138, v138 quad_perm:[2,3,0,1] row_mask:0xf bank_mask:0xf
	v_add_f32_dpp v139, v139, v139 quad_perm:[2,3,0,1] row_mask:0xf bank_mask:0xf
	v_add_f32_dpp v140, v140, v140 quad_perm:[2,3,0,1] row_mask:0xf bank_mask:0xf
	v_add_f32_dpp v141, v141, v141 quad_perm:[2,3,0,1] row_mask:0xf bank_mask:0xf
	v_add_f32_dpp v142, v142, v142 quad_perm:[2,3,0,1] row_mask:0xf bank_mask:0xf
	v_add_f32_dpp v143, v143, v143 quad_perm:[2,3,0,1] row_mask:0xf bank_mask:0xf
	v_add_f32_dpp v144, v144, v144 quad_perm:[2,3,0,1] row_mask:0xf bank_mask:0xf
	v_add_f32_dpp v145, v145, v145 quad_perm:[2,3,0,1] row_mask:0xf bank_mask:0xf
	v_add_f32_dpp v138, v138, v138 row_half_mirror row_mask:0xf bank_mask:0xf
	v_add_f32_dpp v139, v139, v139 row_half_mirror row_mask:0xf bank_mask:0xf
	v_add_f32_dpp v140, v140, v140 row_half_mirror row_mask:0xf bank_mask:0xf
	v_add_f32_dpp v141, v141, v141 row_half_mirror row_mask:0xf bank_mask:0xf
	v_add_f32_dpp v142, v142, v142 row_half_mirror row_mask:0xf bank_mask:0xf
	v_add_f32_dpp v143, v143, v143 row_half_mirror row_mask:0xf bank_mask:0xf
	v_add_f32_dpp v144, v144, v144 row_half_mirror row_mask:0xf bank_mask:0xf
	v_add_f32_dpp v145, v145, v145 row_half_mirror row_mask:0xf bank_mask:0xf
	v_fmac_f32_e32 v146, v138, v148
	v_fmac_f32_e32 v146, v139, v149
	v_fmac_f32_e32 v146, v140, v150
	v_fmac_f32_e32 v146, v141, v151
	v_fmac_f32_e32 v146, v142, v152
	v_fmac_f32_e32 v146, v143, v153
	v_fmac_f32_e32 v146, v144, v154
	v_fmac_f32_e32 v146, v145, v155
	s_waitcnt lgkmcnt(0)
	v_add_u32_e32 v159, v66, v156
	global_load_dwordx4 v[2:5], v159, s[38:39]
	v_add_u32_e32 v159, v67, v156
	global_load_dwordx4 v[6:9], v159, s[38:39]
	v_add_u32_e32 v159, v68, v156
	global_load_dwordx4 v[10:13], v159, s[38:39]
	v_add_u32_e32 v159, v69, v156
	global_load_dwordx4 v[14:17], v159, s[38:39]
	v_add_u32_e32 v159, v70, v156
	global_load_dwordx4 v[18:21], v159, s[38:39]
	v_add_u32_e32 v159, v71, v156
	global_load_dwordx4 v[22:25], v159, s[38:39]
	v_add_u32_e32 v159, v72, v156
	global_load_dwordx4 v[26:29], v159, s[38:39]
	v_add_u32_e32 v159, v73, v156
	global_load_dwordx4 v[30:33], v159, s[38:39]
	s_waitcnt vmcnt(10)
; DEV void phase_peer_expert(const Params& p, int layer, int M, bool final_, int part, char* smem) {
;     ...
;       f32x2 da = (f32x2){0.f, 0.f}, db = (f32x2){0.f, 0.f};
; #pragma unroll
;       for (int c = 0; c < 4; c++) {
;         da = fp8dot4(cur[c][0], xf[c * 8 + 0], xf[c * 8 + 1], da); da = fp8dot4(cur[c][1], xf[c * 8 + 2], xf[c * 8 + 3], da);
;         da = fp8dot4(cur[c][2], xf[c * 8 + 4], xf[c * 8 + 5], da); da = fp8dot4(cur[c][3], xf[c * 8 + 6], xf[c * 8 + 7], da);
;         db = fp8dot4(cur[4 + c][0], xf[c * 8 + 0], xf[c * 8 + 1], db); db = fp8dot4(cur[4 + c][1], xf[c * 8 + 2], xf[c * 8 + 3], db);
;         db = fp8dot4(cur[4 + c][2], xf[c * 8 + 4], xf[c * 8 + 5], db); db = fp8dot4(cur[4 + c][3], xf[c * 8 + 6], xf[c * 8 + 7], db);
;       }
;       float d0 = da.x + da.y, d1 = db.x + db.y;
;       d0 += __shfl_xor(d0, 1); d1 += __shfl_xor(d1, 1);
;       d0 += __shfl_xor(d0, 2); d1 += __shfl_xor(d1, 2);
;       d0 += __shfl_xor(d0, 4); d1 += __shfl_xor(d1, 4);
;       d0 += __shfl_xor(d0, 8); d1 += __shfl_xor(d1, 8);
	v_cvt_pk_f32_fp8_e32 v[122:123], v34
	v_cvt_pk_f32_fp8_e32 v[126:127], v38
	v_cvt_pk_f32_fp8_sdwa v[124:125], v34 src0_sel:WORD_1
	v_cvt_pk_f32_fp8_sdwa v[128:129], v38 src0_sel:WORD_1
	v_pk_fma_f32 v[106:107], v[122:123], v[90:91], 0 op_sel_hi:[1,1,0]
	v_pk_fma_f32 v[108:109], v[126:127], v[90:91], 0 op_sel_hi:[1,1,0]
	v_pk_fma_f32 v[106:107], v[124:125], v[92:93], v[106:107]
	v_pk_fma_f32 v[108:109], v[128:129], v[92:93], v[108:109]
	v_cvt_pk_f32_fp8_e32 v[122:123], v35
	v_cvt_pk_f32_fp8_e32 v[126:127], v39
	v_cvt_pk_f32_fp8_sdwa v[124:125], v35 src0_sel:WORD_1
	v_cvt_pk_f32_fp8_sdwa v[128:129], v39 src0_sel:WORD_1
	v_pk_fma_f32 v[106:107], v[122:123], v[94:95], v[106:107]
	v_pk_fma_f32 v[108:109], v[126:127], v[94:95], v[108:109]
	v_pk_fma_f32 v[106:107], v[124:125], v[96:97], v[106:107]
	v_pk_fma_f32 v[108:109], v[128:129], v[96:97], v[108:109]
	v_cvt_pk_f32_fp8_e32 v[122:123], v36
	v_cvt_pk_f32_fp8_e32 v[126:127], v40
	v_cvt_pk_f32_fp8_sdwa v[124:125], v36 src0_sel:WORD_1
	v_cvt_pk_f32_fp8_sdwa v[128:129], v40 src0_sel:WORD_1
	v_pk_fma_f32 v[106:107], v[122:123], v[98:99], v[106:107]
	v_pk_fma_f32 v[108:109], v[126:127], v[98:99], v[108:109]
	v_pk_fma_f32 v[106:107], v[124:125], v[100:101], v[106:107]
	v_pk_fma_f32 v[108:109], v[128:129], v[100:101], v[108:109]
	v_cvt_pk_f32_fp8_e32 v[122:123], v37
	v_cvt_pk_f32_fp8_e32 v[126:127], v41
	v_cvt_pk_f32_fp8_sdwa v[124:125], v37 src0_sel:WORD_1
	v_cvt_pk_f32_fp8_sdwa v[128:129], v41 src0_sel:WORD_1
	v_pk_fma_f32 v[106:107], v[122:123], v[102:103], v[106:107]
	v_pk_fma_f32 v[108:109], v[126:127], v[102:103], v[108:109]
	v_pk_fma_f32 v[106:107], v[124:125], v[104:105], v[106:107]
	v_pk_fma_f32 v[108:109], v[128:129], v[104:105], v[108:109]
	v_cvt_pk_f32_fp8_e32 v[122:123], v42
	v_cvt_pk_f32_fp8_e32 v[126:127], v46
	v_cvt_pk_f32_fp8_sdwa v[124:125], v42 src0_sel:WORD_1
	v_cvt_pk_f32_fp8_sdwa v[128:129], v46 src0_sel:WORD_1
	v_pk_fma_f32 v[110:111], v[122:123], v[90:91], 0 op_sel_hi:[1,1,0]
	v_pk_fma_f32 v[112:113], v[126:127], v[90:91], 0 op_sel_hi:[1,1,0]
	v_pk_fma_f32 v[110:111], v[124:125], v[92:93], v[110:111]
	v_pk_fma_f32 v[112:113], v[128:129], v[92:93], v[112:113]
	v_cvt_pk_f32_fp8_e32 v[122:123], v43
	v_cvt_pk_f32_fp8_e32 v[126:127], v47
	v_cvt_pk_f32_fp8_sdwa v[124:125], v43 src0_sel:WORD_1
	v_cvt_pk_f32_fp8_sdwa v[128:129], v47 src0_sel:WORD_1
	v_pk_fma_f32 v[110:111], v[122:123], v[94:95], v[110:111]
	v_pk_fma_f32 v[112:113], v[126:127], v[94:95], v[112:113]
	v_pk_fma_f32 v[110:111], v[124:125], v[96:97], v[110:111]
	v_pk_fma_f32 v[112:113], v[128:129], v[96:97], v[112:113]
	v_cvt_pk_f32_fp8_e32 v[122:123], v44
	v_cvt_pk_f32_fp8_e32 v[126:127], v48
	v_cvt_pk_f32_fp8_sdwa v[124:125], v44 src0_sel:WORD_1
	v_cvt_pk_f32_fp8_sdwa v[128:129], v48 src0_sel:WORD_1
	v_pk_fma_f32 v[110:111], v[122:123], v[98:99], v[110:111]
	v_pk_fma_f32 v[112:113], v[126:127], v[98:99], v[112:113]
	v_pk_fma_f32 v[110:111], v[124:125], v[100:101], v[110:111]
	v_pk_fma_f32 v[112:113], v[128:129], v[100:101], v[112:113]
	v_cvt_pk_f32_fp8_e32 v[122:123], v45
	v_cvt_pk_f32_fp8_e32 v[126:127], v49
	v_cvt_pk_f32_fp8_sdwa v[124:125], v45 src0_sel:WORD_1
	v_cvt_pk_f32_fp8_sdwa v[128:129], v49 src0_sel:WORD_1
	v_pk_fma_f32 v[110:111], v[122:123], v[102:103], v[110:111]
	v_pk_fma_f32 v[112:113], v[126:127], v[102:103], v[112:113]
	v_pk_fma_f32 v[110:111], v[124:125], v[104:105], v[110:111]
	v_pk_fma_f32 v[112:113], v[128:129], v[104:105], v[112:113]
	v_cvt_pk_f32_fp8_e32 v[122:123], v50
	v_cvt_pk_f32_fp8_e32 v[126:127], v54
	v_cvt_pk_f32_fp8_sdwa v[124:125], v50 src0_sel:WORD_1
	v_cvt_pk_f32_fp8_sdwa v[128:129], v54 src0_sel:WORD_1
	v_pk_fma_f32 v[114:115], v[122:123], v[90:91], 0 op_sel_hi:[1,1,0]
	v_pk_fma_f32 v[116:117], v[126:127], v[90:91], 0 op_sel_hi:[1,1,0]
	v_pk_fma_f32 v[114:115], v[124:125], v[92:93], v[114:115]
	v_pk_fma_f32 v[116:117], v[128:129], v[92:93], v[116:117]
	v_cvt_pk_f32_fp8_e32 v[122:123], v51
	v_cvt_pk_f32_fp8_e32 v[126:127], v55
	v_cvt_pk_f32_fp8_sdwa v[124:125], v51 src0_sel:WORD_1
	v_cvt_pk_f32_fp8_sdwa v[128:129], v55 src0_sel:WORD_1
	v_pk_fma_f32 v[114:115], v[122:123], v[94:95], v[114:115]
	v_pk_fma_f32 v[116:117], v[126:127], v[94:95], v[116:117]
	v_pk_fma_f32 v[114:115], v[124:125], v[96:97], v[114:115]
	v_pk_fma_f32 v[116:117], v[128:129], v[96:97], v[116:117]
	v_cvt_pk_f32_fp8_e32 v[122:123], v52
	v_cvt_pk_f32_fp8_e32 v[126:127], v56
	v_cvt_pk_f32_fp8_sdwa v[124:125], v52 src0_sel:WORD_1
	v_cvt_pk_f32_fp8_sdwa v[128:129], v56 src0_sel:WORD_1
	v_pk_fma_f32 v[114:115], v[122:123], v[98:99], v[114:115]
	v_pk_fma_f32 v[116:117], v[126:127], v[98:99], v[116:117]
	v_pk_fma_f32 v[114:115], v[124:125], v[100:101], v[114:115]
	v_pk_fma_f32 v[116:117], v[128:129], v[100:101], v[116:117]
	v_cvt_pk_f32_fp8_e32 v[122:123], v53
	v_cvt_pk_f32_fp8_e32 v[126:127], v57
	v_cvt_pk_f32_fp8_sdwa v[124:125], v53 src0_sel:WORD_1
	v_cvt_pk_f32_fp8_sdwa v[128:129], v57 src0_sel:WORD_1
	v_pk_fma_f32 v[114:115], v[122:123], v[102:103], v[114:115]
	v_pk_fma_f32 v[116:117], v[126:127], v[102:103], v[116:117]
	v_pk_fma_f32 v[114:115], v[124:125], v[104:105], v[114:115]
	v_pk_fma_f32 v[116:117], v[128:129], v[104:105], v[116:117]
	v_cvt_pk_f32_fp8_e32 v[122:123], v58
	v_cvt_pk_f32_fp8_e32 v[126:127], v62
	v_cvt_pk_f32_fp8_sdwa v[124:125], v58 src0_sel:WORD_1
	v_cvt_pk_f32_fp8_sdwa v[128:129], v62 src0_sel:WORD_1
	v_pk_fma_f32 v[118:119], v[122:123], v[90:91], 0 op_sel_hi:[1,1,0]
; DEV void phase_peer_expert(const Params& p, int layer, int M, bool final_, int part, char* smem) {
;     ...
;       f32x2 da = (f32x2){0.f, 0.f}, db = (f32x2){0.f, 0.f};
; #pragma unroll
;       for (int c = 0; c < 4; c++) {
;         da = fp8dot4(cur[c][0], xf[c * 8 + 0], xf[c * 8 + 1], da); da = fp8dot4(cur[c][1], xf[c * 8 + 2], xf[c * 8 + 3], da);
;         da = fp8dot4(cur[c][2], xf[c * 8 + 4], xf[c * 8 + 5], da); da = fp8dot4(cur[c][3], xf[c * 8 + 6], xf[c * 8 + 7], da);
;         db = fp8dot4(cur[4 + c][0], xf[c * 8 + 0], xf[c * 8 + 1], db); db = fp8dot4(cur[4 + c][1], xf[c * 8 + 2], xf[c * 8 + 3], db);
;         db = fp8dot4(cur[4 + c][2], xf[c * 8 + 4], xf[c * 8 + 5], db); db = fp8dot4(cur[4 + c][3], xf[c * 8 + 6], xf[c * 8 + 7], db);
;       }
;       float d0 = da.x + da.y, d1 = db.x + db.y;
;       d0 += __shfl_xor(d0, 1); d1 += __shfl_xor(d1, 1);
;       d0 += __shfl_xor(d0, 2); d1 += __shfl_xor(d1, 2);
;       d0 += __shfl_xor(d0, 4); d1 += __shfl_xor(d1, 4);
;       d0 += __shfl_xor(d0, 8); d1 += __shfl_xor(d1, 8);
;       const int s0 = st * 8 + g, s1 = s0 + 4;
;       d0 *= su[s0]; d1 *= su[s1];
;       const float a0 = 0.5f * d0 * (1.f + erff(d0 * 0.70710678118f));
;       const float a1 = 0.5f * d1 * (1.f + erff(d1 * 0.70710678118f));
;       if (l16 == 0) { COEF[(size_t)m * 128 + s0] = sg[s0] * a0; COEF[(size_t)m * 128 + s1] = sg[s1] * a1; }
	v_pk_fma_f32 v[120:121], v[126:127], v[90:91], 0 op_sel_hi:[1,1,0]
	v_pk_fma_f32 v[118:119], v[124:125], v[92:93], v[118:119]
	v_pk_fma_f32 v[120:121], v[128:129], v[92:93], v[120:121]
	v_cvt_pk_f32_fp8_e32 v[122:123], v59
	v_cvt_pk_f32_fp8_e32 v[126:127], v63
	v_cvt_pk_f32_fp8_sdwa v[124:125], v59 src0_sel:WORD_1
	v_cvt_pk_f32_fp8_sdwa v[128:129], v63 src0_sel:WORD_1
	v_pk_fma_f32 v[118:119], v[122:123], v[94:95], v[118:119]
	v_pk_fma_f32 v[120:121], v[126:127], v[94:95], v[120:121]
	v_pk_fma_f32 v[118:119], v[124:125], v[96:97], v[118:119]
	v_pk_fma_f32 v[120:121], v[128:129], v[96:97], v[120:121]
	v_cvt_pk_f32_fp8_e32 v[122:123], v60
	v_cvt_pk_f32_fp8_e32 v[126:127], v64
	v_cvt_pk_f32_fp8_sdwa v[124:125], v60 src0_sel:WORD_1
	v_cvt_pk_f32_fp8_sdwa v[128:129], v64 src0_sel:WORD_1
	v_pk_fma_f32 v[118:119], v[122:123], v[98:99], v[118:119]
	v_pk_fma_f32 v[120:121], v[126:127], v[98:99], v[120:121]
	v_pk_fma_f32 v[118:119], v[124:125], v[100:101], v[118:119]
	v_pk_fma_f32 v[120:121], v[128:129], v[100:101], v[120:121]
	v_cvt_pk_f32_fp8_e32 v[122:123], v61
	v_cvt_pk_f32_fp8_e32 v[126:127], v65
	v_cvt_pk_f32_fp8_sdwa v[124:125], v61 src0_sel:WORD_1
	v_cvt_pk_f32_fp8_sdwa v[128:129], v65 src0_sel:WORD_1
	v_pk_fma_f32 v[118:119], v[122:123], v[102:103], v[118:119]
	v_pk_fma_f32 v[120:121], v[126:127], v[102:103], v[120:121]
	v_pk_fma_f32 v[118:119], v[124:125], v[104:105], v[118:119]
	v_pk_fma_f32 v[120:121], v[128:129], v[104:105], v[120:121]
	s_nop 0
	v_add_f32_e32 v138, v106, v107
	v_add_f32_e32 v139, v108, v109
	v_add_f32_e32 v140, v110, v111
	v_add_f32_e32 v141, v112, v113
	v_add_f32_e32 v142, v114, v115
	v_add_f32_e32 v143, v116, v117
	v_add_f32_e32 v144, v118, v119
	v_add_f32_e32 v145, v120, v121
	s_nop 1
	v_add_f32_dpp v138, v138, v138 quad_perm:[1,0,3,2] row_mask:0xf bank_mask:0xf
	v_add_f32_dpp v139, v139, v139 quad_perm:[1,0,3,2] row_mask:0xf bank_mask:0xf
	v_add_f32_dpp v140, v140, v140 quad_perm:[1,0,3,2] row_mask:0xf bank_mask:0xf
	v_add_f32_dpp v141, v141, v141 quad_perm:[1,0,3,2] row_mask:0xf bank_mask:0xf
	v_add_f32_dpp v142, v142, v142 quad_perm:[1,0,3,2] row_mask:0xf bank_mask:0xf
	v_add_f32_dpp v143, v143, v143 quad_perm:[1,0,3,2] row_mask:0xf bank_mask:0xf
	v_add_f32_dpp v144, v144, v144 quad_perm:[1,0,3,2] row_mask:0xf bank_mask:0xf
	v_add_f32_dpp v145, v145, v145 quad_perm:[1,0,3,2] row_mask:0xf bank_mask:0xf
	v_add_f32_dpp v138, v138, v138 quad_perm:[2,3,0,1] row_mask:0xf bank_mask:0xf
	v_add_f32_dpp v139, v139, v139 quad_perm:[2,3,0,1] row_mask:0xf bank_mask:0xf
	v_add_f32_dpp v140, v140, v140 quad_perm:[2,3,0,1] row_mask:0xf bank_mask:0xf
	v_add_f32_dpp v141, v141, v141 quad_perm:[2,3,0,1] row_mask:0xf bank_mask:0xf
	v_add_f32_dpp v142, v142, v142 quad_perm:[2,3,0,1] row_mask:0xf bank_mask:0xf
	v_add_f32_dpp v143, v143, v143 quad_perm:[2,3,0,1] row_mask:0xf bank_mask:0xf
	v_add_f32_dpp v144, v144, v144 quad_perm:[2,3,0,1] row_mask:0xf bank_mask:0xf
	v_add_f32_dpp v145, v145, v145 quad_perm:[2,3,0,1] row_mask:0xf bank_mask:0xf
	v_add_f32_dpp v138, v138, v138 row_half_mirror row_mask:0xf bank_mask:0xf
	v_add_f32_dpp v139, v139, v139 row_half_mirror row_mask:0xf bank_mask:0xf
	v_add_f32_dpp v140, v140, v140 row_half_mirror row_mask:0xf bank_mask:0xf
	v_add_f32_dpp v141, v141, v141 row_half_mirror row_mask:0xf bank_mask:0xf
	v_add_f32_dpp v142, v142, v142 row_half_mirror row_mask:0xf bank_mask:0xf
	v_add_f32_dpp v143, v143, v143 row_half_mirror row_mask:0xf bank_mask:0xf
	v_add_f32_dpp v144, v144, v144 row_half_mirror row_mask:0xf bank_mask:0xf
	v_add_f32_dpp v145, v145, v145 row_half_mirror row_mask:0xf bank_mask:0xf
	v_fmac_f32_e32 v147, v138, v148
	v_fmac_f32_e32 v147, v139, v149
	v_fmac_f32_e32 v147, v140, v150
	v_fmac_f32_e32 v147, v141, v151
	v_fmac_f32_e32 v147, v142, v152
	v_fmac_f32_e32 v147, v143, v153
	v_fmac_f32_e32 v147, v144, v154
	v_fmac_f32_e32 v147, v145, v155
	v_add_u32_e32 v159, v74, v156
	global_load_dwordx4 v[34:37], v159, s[38:39]
	v_add_u32_e32 v159, v75, v156
	global_load_dwordx4 v[38:41], v159, s[38:39]
	v_add_u32_e32 v159, v76, v156
	global_load_dwordx4 v[42:45], v159, s[38:39]
	v_add_u32_e32 v159, v77, v156
	global_load_dwordx4 v[46:49], v159, s[38:39]
	v_add_u32_e32 v159, v78, v156
	global_load_dwordx4 v[50:53], v159, s[38:39]
	v_add_u32_e32 v159, v79, v156
	global_load_dwordx4 v[54:57], v159, s[38:39]
	v_add_u32_e32 v159, v80, v156
	global_load_dwordx4 v[58:61], v159, s[38:39]
	v_add_u32_e32 v159, v81, v156
	global_load_dwordx4 v[62:65], v159, s[38:39]
	s_lshl_b32 s40, s18, 9
	v_add_u32_e32 v160, s40, v161
	ds_add_f32 v160, v146
	ds_add_f32 v160, v147 offset:256
	s_waitcnt vmcnt(16)
	v_lshlrev_b32_e32 v90, 16, v82
	v_and_b32_e32 v91, 0xffff0000, v82
	v_lshlrev_b32_e32 v92, 16, v83
	v_and_b32_e32 v93, 0xffff0000, v83
	v_lshlrev_b32_e32 v94, 16, v84
	v_and_b32_e32 v95, 0xffff0000, v84
	v_lshlrev_b32_e32 v96, 16, v85
	v_and_b32_e32 v97, 0xffff0000, v85
	v_lshlrev_b32_e32 v98, 16, v86
	v_and_b32_e32 v99, 0xffff0000, v86
	v_lshlrev_b32_e32 v100, 16, v87
	v_and_b32_e32 v101, 0xffff0000, v87
	v_lshlrev_b32_e32 v102, 16, v88
	v_and_b32_e32 v103, 0xffff0000, v88
	v_lshlrev_b32_e32 v104, 16, v89
	v_and_b32_e32 v105, 0xffff0000, v89
	s_mov_b32 s18, s22
	s_mov_b32 s20, s28
	s_add_u32 s22, s22, 1
	s_cmp_lt_u32 s22, s8
	s_cbranch_scc1 .Lu_nx_ok
	s_mov_b32 s22, 0
	s_add_u32 s28, s28, 1
	s_cmp_lt_u32 s28, 8
	s_cbranch_scc1 .Lu_nx_bar
	s_mov_b32 s22, s18
	s_mov_b32 s28, s20
	s_branch .Lu_nx_ok
.Lu_nx_bar:
	s_barrier

; DEV void phase_peer_expert(const Params& p, int layer, int M, bool final_, int part, char* smem) {
;     ...
;     }
;     __syncthreads();
;   }
;   return;
;   }
.Lu_tail_done:
	s_waitcnt vmcnt(0) lgkmcnt(0)
	s_mov_b32 m0, 1
	s_branch .Lpeer_entry

; DEV void phase_peer_expert(const Params& p, int layer, int M, bool final_, int part, char* smem) {
;     ...
;       const float c0 = coefs[st * 8 + g], c1 = coefs[st * 8 + 4 + g];
;       const f32x2 ca = (f32x2){c0, c0}, cb = (f32x2){c1, c1};
; #pragma unroll
;       for (int c = 0; c < 4; c++) {
; #pragma unroll
;         for (int d = 0; d < 4; d++) {
;           acc[c * 8 + d * 2 + 0] += ca * __builtin_amdgcn_cvt_pk_f32_fp8((int)cur[c][d], false);
;           acc[c * 8 + d * 2 + 1] += ca * __builtin_amdgcn_cvt_pk_f32_fp8((int)cur[c][d], true);
;           acc[c * 8 + d * 2 + 0] += cb * __builtin_amdgcn_cvt_pk_f32_fp8((int)cur[4 + c][d], false);
;           acc[c * 8 + d * 2 + 1] += cb * __builtin_amdgcn_cvt_pk_f32_fp8((int)cur[4 + c][d], true);
;         }
;       }
.Lv_loop:
	s_waitcnt vmcnt(11) lgkmcnt(0)
	v_cvt_pk_f32_fp8_e32 v[114:115], v2
	v_cvt_pk_f32_fp8_sdwa v[116:117], v2 src0_sel:WORD_1
	v_pk_fma_f32 v[98:99], v[82:83], v[114:115], 0 op_sel_hi:[0,1,0]
	v_pk_fma_f32 v[100:101], v[82:83], v[116:117], 0 op_sel_hi:[0,1,0]
	v_cvt_pk_f32_fp8_e32 v[118:119], v3
	v_cvt_pk_f32_fp8_sdwa v[120:121], v3 src0_sel:WORD_1
	v_pk_fma_f32 v[102:103], v[82:83], v[118:119], 0 op_sel_hi:[0,1,0]
	v_pk_fma_f32 v[104:105], v[82:83], v[120:121], 0 op_sel_hi:[0,1,0]
	v_cvt_pk_f32_fp8_e32 v[114:115], v4
	v_cvt_pk_f32_fp8_sdwa v[116:117], v4 src0_sel:WORD_1
	v_pk_fma_f32 v[106:107], v[82:83], v[114:115], 0 op_sel_hi:[0,1,0]
	v_pk_fma_f32 v[108:109], v[82:83], v[116:117], 0 op_sel_hi:[0,1,0]
	v_cvt_pk_f32_fp8_e32 v[118:119], v5
	v_cvt_pk_f32_fp8_sdwa v[120:121], v5 src0_sel:WORD_1
	v_pk_fma_f32 v[110:111], v[82:83], v[118:119], 0 op_sel_hi:[0,1,0]
	v_pk_fma_f32 v[112:113], v[82:83], v[120:121], 0 op_sel_hi:[0,1,0]
	v_cvt_pk_f32_fp8_e32 v[114:115], v6
	v_cvt_pk_f32_fp8_sdwa v[116:117], v6 src0_sel:WORD_1
	v_pk_fma_f32 v[98:99], v[82:83], v[114:115], v[98:99] op_sel:[1,0,0] op_sel_hi:[1,1,1]
	v_pk_fma_f32 v[100:101], v[82:83], v[116:117], v[100:101] op_sel:[1,0,0] op_sel_hi:[1,1,1]
	v_cvt_pk_f32_fp8_e32 v[118:119], v7
	v_cvt_pk_f32_fp8_sdwa v[120:121], v7 src0_sel:WORD_1
	v_pk_fma_f32 v[102:103], v[82:83], v[118:119], v[102:103] op_sel:[1,0,0] op_sel_hi:[1,1,1]
	v_pk_fma_f32 v[104:105], v[82:83], v[120:121], v[104:105] op_sel:[1,0,0] op_sel_hi:[1,1,1]
	v_cvt_pk_f32_fp8_e32 v[114:115], v8
	v_cvt_pk_f32_fp8_sdwa v[116:117], v8 src0_sel:WORD_1
	v_pk_fma_f32 v[106:107], v[82:83], v[114:115], v[106:107] op_sel:[1,0,0] op_sel_hi:[1,1,1]
	v_pk_fma_f32 v[108:109], v[82:83], v[116:117], v[108:109] op_sel:[1,0,0] op_sel_hi:[1,1,1]
	v_cvt_pk_f32_fp8_e32 v[118:119], v9
	v_cvt_pk_f32_fp8_sdwa v[120:121], v9 src0_sel:WORD_1
	v_pk_fma_f32 v[110:111], v[82:83], v[118:119], v[110:111] op_sel:[1,0,0] op_sel_hi:[1,1,1]
	v_pk_fma_f32 v[112:113], v[82:83], v[120:121], v[112:113] op_sel:[1,0,0] op_sel_hi:[1,1,1]
	v_cvt_pk_f32_fp8_e32 v[114:115], v10
	v_cvt_pk_f32_fp8_sdwa v[116:117], v10 src0_sel:WORD_1
	v_pk_fma_f32 v[98:99], v[84:85], v[114:115], v[98:99] op_sel_hi:[0,1,1]
	v_pk_fma_f32 v[100:101], v[84:85], v[116:117], v[100:101] op_sel_hi:[0,1,1]
	v_cvt_pk_f32_fp8_e32 v[118:119], v11
	v_cvt_pk_f32_fp8_sdwa v[120:121], v11 src0_sel:WORD_1
	v_pk_fma_f32 v[102:103], v[84:85], v[118:119], v[102:103] op_sel_hi:[0,1,1]
	v_pk_fma_f32 v[104:105], v[84:85], v[120:121], v[104:105] op_sel_hi:[0,1,1]
	v_cvt_pk_f32_fp8_e32 v[114:115], v12
	v_cvt_pk_f32_fp8_sdwa v[116:117], v12 src0_sel:WORD_1
	v_pk_fma_f32 v[106:107], v[84:85], v[114:115], v[106:107] op_sel_hi:[0,1,1]
	v_pk_fma_f32 v[108:109], v[84:85], v[116:117], v[108:109] op_sel_hi:[0,1,1]
	v_cvt_pk_f32_fp8_e32 v[118:119], v13
	v_cvt_pk_f32_fp8_sdwa v[120:121], v13 src0_sel:WORD_1
	v_pk_fma_f32 v[110:111], v[84:85], v[118:119], v[110:111] op_sel_hi:[0,1,1]
	v_pk_fma_f32 v[112:113], v[84:85], v[120:121], v[112:113] op_sel_hi:[0,1,1]
	v_cvt_pk_f32_fp8_e32 v[114:115], v14
	v_cvt_pk_f32_fp8_sdwa v[116:117], v14 src0_sel:WORD_1
	v_pk_fma_f32 v[98:99], v[84:85], v[114:115], v[98:99] op_sel:[1,0,0] op_sel_hi:[1,1,1]
	v_pk_fma_f32 v[100:101], v[84:85], v[116:117], v[100:101] op_sel:[1,0,0] op_sel_hi:[1,1,1]
	v_cvt_pk_f32_fp8_e32 v[118:119], v15
	v_cvt_pk_f32_fp8_sdwa v[120:121], v15 src0_sel:WORD_1
	v_pk_fma_f32 v[102:103], v[84:85], v[118:119], v[102:103] op_sel:[1,0,0] op_sel_hi:[1,1,1]
	v_pk_fma_f32 v[104:105], v[84:85], v[120:121], v[104:105] op_sel:[1,0,0] op_sel_hi:[1,1,1]
	v_cvt_pk_f32_fp8_e32 v[114:115], v16
	v_cvt_pk_f32_fp8_sdwa v[116:117], v16 src0_sel:WORD_1
	v_pk_fma_f32 v[106:107], v[84:85], v[114:115], v[106:107] op_sel:[1,0,0] op_sel_hi:[1,1,1]
	v_pk_fma_f32 v[108:109], v[84:85], v[116:117], v[108:109] op_sel:[1,0,0] op_sel_hi:[1,1,1]
	v_cvt_pk_f32_fp8_e32 v[118:119], v17
	v_cvt_pk_f32_fp8_sdwa v[120:121], v17 src0_sel:WORD_1
	v_pk_fma_f32 v[110:111], v[84:85], v[118:119], v[110:111] op_sel:[1,0,0] op_sel_hi:[1,1,1]
	v_pk_fma_f32 v[112:113], v[84:85], v[120:121], v[112:113] op_sel:[1,0,0] op_sel_hi:[1,1,1]
	v_cvt_pk_f32_fp8_e32 v[114:115], v18
	v_cvt_pk_f32_fp8_sdwa v[116:117], v18 src0_sel:WORD_1
	v_pk_fma_f32 v[98:99], v[86:87], v[114:115], v[98:99] op_sel_hi:[0,1,1]
	v_pk_fma_f32 v[100:101], v[86:87], v[116:117], v[100:101] op_sel_hi:[0,1,1]
	v_cvt_pk_f32_fp8_e32 v[118:119], v19
	v_cvt_pk_f32_fp8_sdwa v[120:121], v19 src0_sel:WORD_1
	v_pk_fma_f32 v[102:103], v[86:87], v[118:119], v[102:103] op_sel_hi:[0,1,1]
	v_pk_fma_f32 v[104:105], v[86:87], v[120:121], v[104:105] op_sel_hi:[0,1,1]
	v_cvt_pk_f32_fp8_e32 v[114:115], v20
	v_cvt_pk_f32_fp8_sdwa v[116:117], v20 src0_sel:WORD_1
	v_pk_fma_f32 v[106:107], v[86:87], v[114:115], v[106:107] op_sel_hi:[0,1,1]
	v_pk_fma_f32 v[108:109], v[86:87], v[116:117], v[108:109] op_sel_hi:[0,1,1]
	v_cvt_pk_f32_fp8_e32 v[118:119], v21
	v_cvt_pk_f32_fp8_sdwa v[120:121], v21 src0_sel:WORD_1
	v_pk_fma_f32 v[110:111], v[86:87], v[118:119], v[110:111] op_sel_hi:[0,1,1]
	v_pk_fma_f32 v[112:113], v[86:87], v[120:121], v[112:113] op_sel_hi:[0,1,1]
	v_cvt_pk_f32_fp8_e32 v[114:115], v22
	v_cvt_pk_f32_fp8_sdwa v[116:117], v22 src0_sel:WORD_1
	v_pk_fma_f32 v[98:99], v[86:87], v[114:115], v[98:99] op_sel:[1,0,0] op_sel_hi:[1,1,1]
	v_pk_fma_f32 v[100:101], v[86:87], v[116:117], v[100:101] op_sel:[1,0,0] op_sel_hi:[1,1,1]
	v_cvt_pk_f32_fp8_e32 v[118:119], v23
	v_cvt_pk_f32_fp8_sdwa v[120:121], v23 src0_sel:WORD_1
	v_pk_fma_f32 v[102:103], v[86:87], v[118:119], v[102:103] op_sel:[1,0,0] op_sel_hi:[1,1,1]
	v_pk_fma_f32 v[104:105], v[86:87], v[120:121], v[104:105] op_sel:[1,0,0] op_sel_hi:[1,1,1]
; DEV void phase_peer_expert(const Params& p, int layer, int M, bool final_, int part, char* smem) {
;     ...
; #pragma unroll 2
;     for (int st = 0; st < 16; st++) {
;       if (st + 1 < 16) {
;         const unsigned char* r0p = V + (size_t)se[(st + 1) * 8 + g] * 1024 + l16 * 16;
;         const unsigned char* r1p = V + (size_t)se[(st + 1) * 8 + 4 + g] * 1024 + l16 * 16;
; #pragma unroll
;         for (int c = 0; c < 4; c++) { nxt[c] = *(const u32x4*)(r0p + c * 256); nxt[4 + c] = *(const u32x4*)(r1p + c * 256); }
;       }
;       const float c0 = coefs[st * 8 + g], c1 = coefs[st * 8 + 4 + g];
;       const f32x2 ca = (f32x2){c0, c0}, cb = (f32x2){c1, c1};
; #pragma unroll
;       for (int c = 0; c < 4; c++) {
; #pragma unroll
;         for (int d = 0; d < 4; d++) {
;           acc[c * 8 + d * 2 + 0] += ca * __builtin_amdgcn_cvt_pk_f32_fp8((int)cur[c][d], false);
;           acc[c * 8 + d * 2 + 1] += ca * __builtin_amdgcn_cvt_pk_f32_fp8((int)cur[c][d], true);
;           acc[c * 8 + d * 2 + 0] += cb * __builtin_amdgcn_cvt_pk_f32_fp8((int)cur[4 + c][d], false);
;           acc[c * 8 + d * 2 + 1] += cb * __builtin_amdgcn_cvt_pk_f32_fp8((int)cur[4 + c][d], true);
;         }
;       }
	v_cvt_pk_f32_fp8_e32 v[114:115], v24
	v_cvt_pk_f32_fp8_sdwa v[116:117], v24 src0_sel:WORD_1
	v_pk_fma_f32 v[106:107], v[86:87], v[114:115], v[106:107] op_sel:[1,0,0] op_sel_hi:[1,1,1]
	v_pk_fma_f32 v[108:109], v[86:87], v[116:117], v[108:109] op_sel:[1,0,0] op_sel_hi:[1,1,1]
	v_cvt_pk_f32_fp8_e32 v[118:119], v25
	v_cvt_pk_f32_fp8_sdwa v[120:121], v25 src0_sel:WORD_1
	v_pk_fma_f32 v[110:111], v[86:87], v[118:119], v[110:111] op_sel:[1,0,0] op_sel_hi:[1,1,1]
	v_pk_fma_f32 v[112:113], v[86:87], v[120:121], v[112:113] op_sel:[1,0,0] op_sel_hi:[1,1,1]
	v_cvt_pk_f32_fp8_e32 v[114:115], v26
	v_cvt_pk_f32_fp8_sdwa v[116:117], v26 src0_sel:WORD_1
	v_pk_fma_f32 v[98:99], v[88:89], v[114:115], v[98:99] op_sel_hi:[0,1,1]
	v_pk_fma_f32 v[100:101], v[88:89], v[116:117], v[100:101] op_sel_hi:[0,1,1]
	v_cvt_pk_f32_fp8_e32 v[118:119], v27
	v_cvt_pk_f32_fp8_sdwa v[120:121], v27 src0_sel:WORD_1
	v_pk_fma_f32 v[102:103], v[88:89], v[118:119], v[102:103] op_sel_hi:[0,1,1]
	v_pk_fma_f32 v[104:105], v[88:89], v[120:121], v[104:105] op_sel_hi:[0,1,1]
	v_cvt_pk_f32_fp8_e32 v[114:115], v28
	v_cvt_pk_f32_fp8_sdwa v[116:117], v28 src0_sel:WORD_1
	v_pk_fma_f32 v[106:107], v[88:89], v[114:115], v[106:107] op_sel_hi:[0,1,1]
	v_pk_fma_f32 v[108:109], v[88:89], v[116:117], v[108:109] op_sel_hi:[0,1,1]
	v_cvt_pk_f32_fp8_e32 v[118:119], v29
	v_cvt_pk_f32_fp8_sdwa v[120:121], v29 src0_sel:WORD_1
	v_pk_fma_f32 v[110:111], v[88:89], v[118:119], v[110:111] op_sel_hi:[0,1,1]
	v_pk_fma_f32 v[112:113], v[88:89], v[120:121], v[112:113] op_sel_hi:[0,1,1]
	v_cvt_pk_f32_fp8_e32 v[114:115], v30
	v_cvt_pk_f32_fp8_sdwa v[116:117], v30 src0_sel:WORD_1
	v_pk_fma_f32 v[98:99], v[88:89], v[114:115], v[98:99] op_sel:[1,0,0] op_sel_hi:[1,1,1]
	v_pk_fma_f32 v[100:101], v[88:89], v[116:117], v[100:101] op_sel:[1,0,0] op_sel_hi:[1,1,1]
	v_cvt_pk_f32_fp8_e32 v[118:119], v31
	v_cvt_pk_f32_fp8_sdwa v[120:121], v31 src0_sel:WORD_1
	v_pk_fma_f32 v[102:103], v[88:89], v[118:119], v[102:103] op_sel:[1,0,0] op_sel_hi:[1,1,1]
	v_pk_fma_f32 v[104:105], v[88:89], v[120:121], v[104:105] op_sel:[1,0,0] op_sel_hi:[1,1,1]
	v_cvt_pk_f32_fp8_e32 v[114:115], v32
	v_cvt_pk_f32_fp8_sdwa v[116:117], v32 src0_sel:WORD_1
	v_pk_fma_f32 v[106:107], v[88:89], v[114:115], v[106:107] op_sel:[1,0,0] op_sel_hi:[1,1,1]
	v_pk_fma_f32 v[108:109], v[88:89], v[116:117], v[108:109] op_sel:[1,0,0] op_sel_hi:[1,1,1]
	v_cvt_pk_f32_fp8_e32 v[118:119], v33
	v_cvt_pk_f32_fp8_sdwa v[120:121], v33 src0_sel:WORD_1
	v_pk_fma_f32 v[110:111], v[88:89], v[118:119], v[110:111] op_sel:[1,0,0] op_sel_hi:[1,1,1]
	v_pk_fma_f32 v[112:113], v[88:89], v[120:121], v[112:113] op_sel:[1,0,0] op_sel_hi:[1,1,1]
	v_add_u32_e32 v159, v66, v156
	global_load_dwordx4 v[2:5], v159, s[38:39]
	v_add_u32_e32 v159, v67, v156
	global_load_dwordx4 v[6:9], v159, s[38:39]
	v_add_u32_e32 v159, v68, v156
	global_load_dwordx4 v[10:13], v159, s[38:39]
	v_add_u32_e32 v159, v69, v156
	global_load_dwordx4 v[14:17], v159, s[38:39]
	v_add_u32_e32 v159, v70, v156
	global_load_dwordx4 v[18:21], v159, s[38:39]
	v_add_u32_e32 v159, v71, v156
	global_load_dwordx4 v[22:25], v159, s[38:39]
	v_add_u32_e32 v159, v72, v156
	global_load_dwordx4 v[26:29], v159, s[38:39]
	v_add_u32_e32 v159, v73, v156
	global_load_dwordx4 v[30:33], v159, s[38:39]
	s_waitcnt vmcnt(11)
	v_cvt_pk_f32_fp8_e32 v[114:115], v34
	v_cvt_pk_f32_fp8_sdwa v[116:117], v34 src0_sel:WORD_1
	v_pk_fma_f32 v[98:99], v[90:91], v[114:115], v[98:99] op_sel_hi:[0,1,1]
	v_pk_fma_f32 v[100:101], v[90:91], v[116:117], v[100:101] op_sel_hi:[0,1,1]
	v_cvt_pk_f32_fp8_e32 v[118:119], v35
	v_cvt_pk_f32_fp8_sdwa v[120:121], v35 src0_sel:WORD_1
	v_pk_fma_f32 v[102:103], v[90:91], v[118:119], v[102:103] op_sel_hi:[0,1,1]
	v_pk_fma_f32 v[104:105], v[90:91], v[120:121], v[104:105] op_sel_hi:[0,1,1]
	v_cvt_pk_f32_fp8_e32 v[114:115], v36
	v_cvt_pk_f32_fp8_sdwa v[116:117], v36 src0_sel:WORD_1
	v_pk_fma_f32 v[106:107], v[90:91], v[114:115], v[106:107] op_sel_hi:[0,1,1]
	v_pk_fma_f32 v[108:109], v[90:91], v[116:117], v[108:109] op_sel_hi:[0,1,1]
	v_cvt_pk_f32_fp8_e32 v[118:119], v37
	v_cvt_pk_f32_fp8_sdwa v[120:121], v37 src0_sel:WORD_1
	v_pk_fma_f32 v[110:111], v[90:91], v[118:119], v[110:111] op_sel_hi:[0,1,1]
	v_pk_fma_f32 v[112:113], v[90:91], v[120:121], v[112:113] op_sel_hi:[0,1,1]
	v_cvt_pk_f32_fp8_e32 v[114:115], v38
	v_cvt_pk_f32_fp8_sdwa v[116:117], v38 src0_sel:WORD_1
	v_pk_fma_f32 v[98:99], v[90:91], v[114:115], v[98:99] op_sel:[1,0,0] op_sel_hi:[1,1,1]
	v_pk_fma_f32 v[100:101], v[90:91], v[116:117], v[100:101] op_sel:[1,0,0] op_sel_hi:[1,1,1]
	v_cvt_pk_f32_fp8_e32 v[118:119], v39
	v_cvt_pk_f32_fp8_sdwa v[120:121], v39 src0_sel:WORD_1
	v_pk_fma_f32 v[102:103], v[90:91], v[118:119], v[102:103] op_sel:[1,0,0] op_sel_hi:[1,1,1]
	v_pk_fma_f32 v[104:105], v[90:91], v[120:121], v[104:105] op_sel:[1,0,0] op_sel_hi:[1,1,1]
	v_cvt_pk_f32_fp8_e32 v[114:115], v40
	v_cvt_pk_f32_fp8_sdwa v[116:117], v40 src0_sel:WORD_1
	v_pk_fma_f32 v[106:107], v[90:91], v[114:115], v[106:107] op_sel:[1,0,0] op_sel_hi:[1,1,1]
	v_pk_fma_f32 v[108:109], v[90:91], v[116:117], v[108:109] op_sel:[1,0,0] op_sel_hi:[1,1,1]
	v_cvt_pk_f32_fp8_e32 v[118:119], v41
	v_cvt_pk_f32_fp8_sdwa v[120:121], v41 src0_sel:WORD_1
	v_pk_fma_f32 v[110:111], v[90:91], v[118:119], v[110:111] op_sel:[1,0,0] op_sel_hi:[1,1,1]
	v_pk_fma_f32 v[112:113], v[90:91], v[120:121], v[112:113] op_sel:[1,0,0] op_sel_hi:[1,1,1]
	v_cvt_pk_f32_fp8_e32 v[114:115], v42
	v_cvt_pk_f32_fp8_sdwa v[116:117], v42 src0_sel:WORD_1
	v_pk_fma_f32 v[98:99], v[92:93], v[114:115], v[98:99] op_sel_hi:[0,1,1]
	v_pk_fma_f32 v[100:101], v[92:93], v[116:117], v[100:101] op_sel_hi:[0,1,1]
	v_cvt_pk_f32_fp8_e32 v[118:119], v43
; DEV void phase_peer_expert(const Params& p, int layer, int M, bool final_, int part, char* smem) {
;     ...
;       const float c0 = coefs[st * 8 + g], c1 = coefs[st * 8 + 4 + g];
;       const f32x2 ca = (f32x2){c0, c0}, cb = (f32x2){c1, c1};
; #pragma unroll
;       for (int c = 0; c < 4; c++) {
; #pragma unroll
;         for (int d = 0; d < 4; d++) {
;           acc[c * 8 + d * 2 + 0] += ca * __builtin_amdgcn_cvt_pk_f32_fp8((int)cur[c][d], false);
;           acc[c * 8 + d * 2 + 1] += ca * __builtin_amdgcn_cvt_pk_f32_fp8((int)cur[c][d], true);
;           acc[c * 8 + d * 2 + 0] += cb * __builtin_amdgcn_cvt_pk_f32_fp8((int)cur[4 + c][d], false);
;           acc[c * 8 + d * 2 + 1] += cb * __builtin_amdgcn_cvt_pk_f32_fp8((int)cur[4 + c][d], true);
;         }
;       }
	v_cvt_pk_f32_fp8_sdwa v[120:121], v43 src0_sel:WORD_1
	v_pk_fma_f32 v[102:103], v[92:93], v[118:119], v[102:103] op_sel_hi:[0,1,1]
	v_pk_fma_f32 v[104:105], v[92:93], v[120:121], v[104:105] op_sel_hi:[0,1,1]
	v_cvt_pk_f32_fp8_e32 v[114:115], v44
	v_cvt_pk_f32_fp8_sdwa v[116:117], v44 src0_sel:WORD_1
	v_pk_fma_f32 v[106:107], v[92:93], v[114:115], v[106:107] op_sel_hi:[0,1,1]
	v_pk_fma_f32 v[108:109], v[92:93], v[116:117], v[108:109] op_sel_hi:[0,1,1]
	v_cvt_pk_f32_fp8_e32 v[118:119], v45
	v_cvt_pk_f32_fp8_sdwa v[120:121], v45 src0_sel:WORD_1
	v_pk_fma_f32 v[110:111], v[92:93], v[118:119], v[110:111] op_sel_hi:[0,1,1]
	v_pk_fma_f32 v[112:113], v[92:93], v[120:121], v[112:113] op_sel_hi:[0,1,1]
	v_cvt_pk_f32_fp8_e32 v[114:115], v46
	v_cvt_pk_f32_fp8_sdwa v[116:117], v46 src0_sel:WORD_1
	v_pk_fma_f32 v[98:99], v[92:93], v[114:115], v[98:99] op_sel:[1,0,0] op_sel_hi:[1,1,1]
	v_pk_fma_f32 v[100:101], v[92:93], v[116:117], v[100:101] op_sel:[1,0,0] op_sel_hi:[1,1,1]
	v_cvt_pk_f32_fp8_e32 v[118:119], v47
	v_cvt_pk_f32_fp8_sdwa v[120:121], v47 src0_sel:WORD_1
	v_pk_fma_f32 v[102:103], v[92:93], v[118:119], v[102:103] op_sel:[1,0,0] op_sel_hi:[1,1,1]
	v_pk_fma_f32 v[104:105], v[92:93], v[120:121], v[104:105] op_sel:[1,0,0] op_sel_hi:[1,1,1]
	v_cvt_pk_f32_fp8_e32 v[114:115], v48
	v_cvt_pk_f32_fp8_sdwa v[116:117], v48 src0_sel:WORD_1
	v_pk_fma_f32 v[106:107], v[92:93], v[114:115], v[106:107] op_sel:[1,0,0] op_sel_hi:[1,1,1]
	v_pk_fma_f32 v[108:109], v[92:93], v[116:117], v[108:109] op_sel:[1,0,0] op_sel_hi:[1,1,1]
	v_cvt_pk_f32_fp8_e32 v[118:119], v49
	v_cvt_pk_f32_fp8_sdwa v[120:121], v49 src0_sel:WORD_1
	v_pk_fma_f32 v[110:111], v[92:93], v[118:119], v[110:111] op_sel:[1,0,0] op_sel_hi:[1,1,1]
	v_pk_fma_f32 v[112:113], v[92:93], v[120:121], v[112:113] op_sel:[1,0,0] op_sel_hi:[1,1,1]
	v_cvt_pk_f32_fp8_e32 v[114:115], v50
	v_cvt_pk_f32_fp8_sdwa v[116:117], v50 src0_sel:WORD_1
	v_pk_fma_f32 v[98:99], v[94:95], v[114:115], v[98:99] op_sel_hi:[0,1,1]
	v_pk_fma_f32 v[100:101], v[94:95], v[116:117], v[100:101] op_sel_hi:[0,1,1]
	v_cvt_pk_f32_fp8_e32 v[118:119], v51
	v_cvt_pk_f32_fp8_sdwa v[120:121], v51 src0_sel:WORD_1
	v_pk_fma_f32 v[102:103], v[94:95], v[118:119], v[102:103] op_sel_hi:[0,1,1]
	v_pk_fma_f32 v[104:105], v[94:95], v[120:121], v[104:105] op_sel_hi:[0,1,1]
	v_cvt_pk_f32_fp8_e32 v[114:115], v52
	v_cvt_pk_f32_fp8_sdwa v[116:117], v52 src0_sel:WORD_1
	v_pk_fma_f32 v[106:107], v[94:95], v[114:115], v[106:107] op_sel_hi:[0,1,1]
	v_pk_fma_f32 v[108:109], v[94:95], v[116:117], v[108:109] op_sel_hi:[0,1,1]
	v_cvt_pk_f32_fp8_e32 v[118:119], v53
	v_cvt_pk_f32_fp8_sdwa v[120:121], v53 src0_sel:WORD_1
	v_pk_fma_f32 v[110:111], v[94:95], v[118:119], v[110:111] op_sel_hi:[0,1,1]
	v_pk_fma_f32 v[112:113], v[94:95], v[120:121], v[112:113] op_sel_hi:[0,1,1]
	v_cvt_pk_f32_fp8_e32 v[114:115], v54
	v_cvt_pk_f32_fp8_sdwa v[116:117], v54 src0_sel:WORD_1
	v_pk_fma_f32 v[98:99], v[94:95], v[114:115], v[98:99] op_sel:[1,0,0] op_sel_hi:[1,1,1]
	v_pk_fma_f32 v[100:101], v[94:95], v[116:117], v[100:101] op_sel:[1,0,0] op_sel_hi:[1,1,1]
	v_cvt_pk_f32_fp8_e32 v[118:119], v55
	v_cvt_pk_f32_fp8_sdwa v[120:121], v55 src0_sel:WORD_1
	v_pk_fma_f32 v[102:103], v[94:95], v[118:119], v[102:103] op_sel:[1,0,0] op_sel_hi:[1,1,1]
	v_pk_fma_f32 v[104:105], v[94:95], v[120:121], v[104:105] op_sel:[1,0,0] op_sel_hi:[1,1,1]
	v_cvt_pk_f32_fp8_e32 v[114:115], v56
	v_cvt_pk_f32_fp8_sdwa v[116:117], v56 src0_sel:WORD_1
	v_pk_fma_f32 v[106:107], v[94:95], v[114:115], v[106:107] op_sel:[1,0,0] op_sel_hi:[1,1,1]
	v_pk_fma_f32 v[108:109], v[94:95], v[116:117], v[108:109] op_sel:[1,0,0] op_sel_hi:[1,1,1]
	v_cvt_pk_f32_fp8_e32 v[118:119], v57
	v_cvt_pk_f32_fp8_sdwa v[120:121], v57 src0_sel:WORD_1
	v_pk_fma_f32 v[110:111], v[94:95], v[118:119], v[110:111] op_sel:[1,0,0] op_sel_hi:[1,1,1]
	v_pk_fma_f32 v[112:113], v[94:95], v[120:121], v[112:113] op_sel:[1,0,0] op_sel_hi:[1,1,1]
	v_cvt_pk_f32_fp8_e32 v[114:115], v58
	v_cvt_pk_f32_fp8_sdwa v[116:117], v58 src0_sel:WORD_1
	v_pk_fma_f32 v[98:99], v[96:97], v[114:115], v[98:99] op_sel_hi:[0,1,1]
	v_pk_fma_f32 v[100:101], v[96:97], v[116:117], v[100:101] op_sel_hi:[0,1,1]
; DEV void phase_peer_expert(const Params& p, int layer, int M, bool final_, int part, char* smem) {
;     ...
;       const float c0 = coefs[st * 8 + g], c1 = coefs[st * 8 + 4 + g];
;       const f32x2 ca = (f32x2){c0, c0}, cb = (f32x2){c1, c1};
; #pragma unroll
;       for (int c = 0; c < 4; c++) {
; #pragma unroll
;         for (int d = 0; d < 4; d++) {
;           acc[c * 8 + d * 2 + 0] += ca * __builtin_amdgcn_cvt_pk_f32_fp8((int)cur[c][d], false);
;           acc[c * 8 + d * 2 + 1] += ca * __builtin_amdgcn_cvt_pk_f32_fp8((int)cur[c][d], true);
;           acc[c * 8 + d * 2 + 0] += cb * __builtin_amdgcn_cvt_pk_f32_fp8((int)cur[4 + c][d], false);
;           acc[c * 8 + d * 2 + 1] += cb * __builtin_amdgcn_cvt_pk_f32_fp8((int)cur[4 + c][d], true);
;         }
;       }
; #pragma unroll
;       for (int c = 0; c < 8; c++) cur[c] = nxt[c];
;     }
;     __syncthreads();
; #pragma unroll
;     for (int i = 0; i < 32; i++) {
;       acc[i].x += __shfl_xor(acc[i].x, 16); acc[i].x += __shfl_xor(acc[i].x, 32);
;       acc[i].y += __shfl_xor(acc[i].y, 16); acc[i].y += __shfl_xor(acc[i].y, 32);
;     }
;     const int mr = (m < MM) ? (m >> 13) : 2;
;     const float* m5 = mod + (size_t)mr * 6144 + 5 * 1024;
;     float xn[16];
; #pragma unroll
;     for (int c = 0; c < 4; c++) {
;       if (c == g) {
; #pragma unroll
;         for (int i = 0; i < 8; i++) { xn[2 * i] = acc[c * 8 + i].x; xn[2 * i + 1] = acc[c * 8 + i].y; }
;       }
;     }
;     const int col = g * 256 + l16 * 16;
;     float ss = 0.f;
; #pragma unroll
;     for (int q = 0; q < 4; q++) {
;       float4 xa = *(const float4*)(X + (size_t)m * 1024 + col + q * 4);
;       float4 ma = *(const float4*)(m5 + col + q * 4);
;       xn[q * 4 + 0] = xa.x + ma.x * xn[q * 4 + 0]; xn[q * 4 + 1] = xa.y + ma.y * xn[q * 4 + 1];
;       xn[q * 4 + 2] = xa.z + ma.z * xn[q * 4 + 2]; xn[q * 4 + 3] = xa.w + ma.w * xn[q * 4 + 3];
;     }
; #pragma unroll
;     for (int i = 0; i < 16; i++) ss += xn[i] * xn[i];
;     if (!final_) {
; #pragma unroll
;       for (int q = 0; q < 4; q++)
;         *(float4*)(X + (size_t)m * 1024 + col + q * 4) = make_float4(xn[q * 4 + 0], xn[q * 4 + 1], xn[q * 4 + 2], xn[q * 4 + 3]);
;       ss = wave_sum(ss);
	v_cvt_pk_f32_fp8_e32 v[118:119], v59
	v_cvt_pk_f32_fp8_sdwa v[120:121], v59 src0_sel:WORD_1
	v_pk_fma_f32 v[102:103], v[96:97], v[118:119], v[102:103] op_sel_hi:[0,1,1]
	v_pk_fma_f32 v[104:105], v[96:97], v[120:121], v[104:105] op_sel_hi:[0,1,1]
	v_cvt_pk_f32_fp8_e32 v[114:115], v60
	v_cvt_pk_f32_fp8_sdwa v[116:117], v60 src0_sel:WORD_1
	v_pk_fma_f32 v[106:107], v[96:97], v[114:115], v[106:107] op_sel_hi:[0,1,1]
	v_pk_fma_f32 v[108:109], v[96:97], v[116:117], v[108:109] op_sel_hi:[0,1,1]
	v_cvt_pk_f32_fp8_e32 v[118:119], v61
	v_cvt_pk_f32_fp8_sdwa v[120:121], v61 src0_sel:WORD_1
	v_pk_fma_f32 v[110:111], v[96:97], v[118:119], v[110:111] op_sel_hi:[0,1,1]
	v_pk_fma_f32 v[112:113], v[96:97], v[120:121], v[112:113] op_sel_hi:[0,1,1]
	v_cvt_pk_f32_fp8_e32 v[114:115], v62
	v_cvt_pk_f32_fp8_sdwa v[116:117], v62 src0_sel:WORD_1
	v_pk_fma_f32 v[98:99], v[96:97], v[114:115], v[98:99] op_sel:[1,0,0] op_sel_hi:[1,1,1]
	v_pk_fma_f32 v[100:101], v[96:97], v[116:117], v[100:101] op_sel:[1,0,0] op_sel_hi:[1,1,1]
	v_cvt_pk_f32_fp8_e32 v[118:119], v63
	v_cvt_pk_f32_fp8_sdwa v[120:121], v63 src0_sel:WORD_1
	v_pk_fma_f32 v[102:103], v[96:97], v[118:119], v[102:103] op_sel:[1,0,0] op_sel_hi:[1,1,1]
	v_pk_fma_f32 v[104:105], v[96:97], v[120:121], v[104:105] op_sel:[1,0,0] op_sel_hi:[1,1,1]
	v_cvt_pk_f32_fp8_e32 v[114:115], v64
	v_cvt_pk_f32_fp8_sdwa v[116:117], v64 src0_sel:WORD_1
	v_pk_fma_f32 v[106:107], v[96:97], v[114:115], v[106:107] op_sel:[1,0,0] op_sel_hi:[1,1,1]
	v_pk_fma_f32 v[108:109], v[96:97], v[116:117], v[108:109] op_sel:[1,0,0] op_sel_hi:[1,1,1]
	v_cvt_pk_f32_fp8_e32 v[118:119], v65
	v_cvt_pk_f32_fp8_sdwa v[120:121], v65 src0_sel:WORD_1
	v_pk_fma_f32 v[110:111], v[96:97], v[118:119], v[110:111] op_sel:[1,0,0] op_sel_hi:[1,1,1]
	v_pk_fma_f32 v[112:113], v[96:97], v[120:121], v[112:113] op_sel:[1,0,0] op_sel_hi:[1,1,1]
	v_add_u32_e32 v159, v74, v156
	global_load_dwordx4 v[34:37], v159, s[38:39]
	v_add_u32_e32 v159, v75, v156
	global_load_dwordx4 v[38:41], v159, s[38:39]
	v_add_u32_e32 v159, v76, v156
	global_load_dwordx4 v[42:45], v159, s[38:39]
	v_add_u32_e32 v159, v77, v156
	global_load_dwordx4 v[46:49], v159, s[38:39]
	v_add_u32_e32 v159, v78, v156
	global_load_dwordx4 v[50:53], v159, s[38:39]
	v_add_u32_e32 v159, v79, v156
	global_load_dwordx4 v[54:57], v159, s[38:39]
	v_add_u32_e32 v159, v80, v156
	global_load_dwordx4 v[58:61], v159, s[38:39]
	v_add_u32_e32 v159, v81, v156
	global_load_dwordx4 v[62:65], v159, s[38:39]
	s_nop 0
	ds_write_b128 v169, v[98:101] offset:0
	ds_write_b128 v169, v[102:105] offset:128
	ds_write_b128 v169, v[106:109] offset:256
	ds_write_b128 v169, v[110:113] offset:384
	ds_read_b64 v[126:127], v170 offset:0
	ds_read_b64 v[128:129], v170 offset:512
	ds_read_b64 v[130:131], v170 offset:1024
	ds_read_b64 v[132:133], v170 offset:1536
	ds_read_b64 v[134:135], v170 offset:2048
	ds_read_b64 v[136:137], v170 offset:2560
	ds_read_b64 v[138:139], v170 offset:3072
	ds_read_b64 v[140:141], v170 offset:3584
	v_add_u32_e32 v160, s32, v172
	ds_read_b128 v[82:85], v160 offset:0
	ds_read_b128 v[86:89], v160 offset:16
	ds_read_b128 v[90:93], v160 offset:32
	ds_read_b128 v[94:97], v160 offset:48
	s_waitcnt lgkmcnt(4)
	v_pk_add_f32 v[126:127], v[126:127], v[128:129]
	v_pk_add_f32 v[130:131], v[130:131], v[132:133]
	v_pk_add_f32 v[134:135], v[134:135], v[136:137]
	v_pk_add_f32 v[138:139], v[138:139], v[140:141]
	s_nop 0
	v_pk_add_f32 v[126:127], v[126:127], v[130:131]
	v_pk_add_f32 v[134:135], v[134:135], v[138:139]
	s_nop 1
	v_pk_add_f32 v[126:127], v[126:127], v[134:135]
	s_waitcnt vmcnt(16)
	s_nop 0
	v_fmac_f32_e32 v122, v124, v126
	v_fmac_f32_e32 v123, v125, v127
	v_add_u32_e32 v173, s41, v168
	global_store_dwordx2 v173, v[122:123], s[0:1]
	v_mul_f32_e32 v174, v122, v122
	v_fmac_f32_e32 v174, v123, v123
	s_lshl_b32 s40, s18, 8
	v_add_u32_e32 v160, s40, v171
	ds_add_f32 v160, v174
	s_mov_b32 s18, s22
	s_mov_b32 s20, s28
	s_add_u32 s22, s22, 1
	s_cmp_lt_u32 s22, s8
	s_cbranch_scc1 .Lv_nx_ok
	s_mov_b32 s22, 0
	s_add_u32 s28, s28, 1
	s_cmp_lt_u32 s28, 8
	s_cbranch_scc1 .Lv_nx_bar
	s_mov_b32 s22, s18
	s_mov_b32 s28, s20
	s_branch .Lv_nx_ok

; DEV int tidx() { int t = threadIdx.x; asm volatile("" : "+v"(t)); return t; }
; DEV void attn_item(const Params& p, int item, char* smem) {
;   const int tid = tidx(), lane = tid & 63, w = tid >> 6, c31 = lane & 31, hf = lane >> 5;
;   const bf16_t* Qb; int nkeys; size_t out_row0; int bh;
;   if (item < 512) {
;     const int xcd = item & 7, j = item >> 3;
;     bh = xcd * 2 + (j >> 5); int q0 = (j & 31) * 256;
;     Qb = WSP(bf16_t, R_Q) + ((size_t)bh * 8192 + q0) * 96; nkeys = 8448; out_row0 = (size_t)(bh >> 3) * 8192 + q0;
;   } else {
;     bh = item - 512;
;     Qb = WSP(bf16_t, R_QC) + ((size_t)bh * 256) * 96; nkeys = 256; out_row0 = (size_t)MM + (bh >> 3) * 256;
;   }
;   const int h = bh & 7;
;   const bf16_t* Kb = WSP(bf16_t, R_K) + (size_t)bh * 8448 * 96;
;   const bf16_t* Vb = WSP(bf16_t, R_VT) + (size_t)bh * 64 * 8448;
;   bf16_t* Ks = (bf16_t*)smem;
;   bf16_t* Vs = Ks + 2 * 32 * ASTR;
.LBB0_740:
	s_andn2_b64 vcc, exec, s[0:1]
	s_cbranch_vccnz .LBB0_771
	v_readlane_b32 s0, v252, 54
	v_readlane_b32 s1, v252, 55
	s_andn2_b64 vcc, exec, s[0:1]
	s_cbranch_vccnz .LBB0_771
	s_cmp_lt_u32 s51, 0x100
	s_cbranch_scc1 .Lattn_noprio
	s_setprio 1
.Lattn_noprio:
	s_add_u32 s16, s28, 0x16c00000
	s_addc_u32 s17, s29, 0
	s_add_u32 s18, s28, 0x15400000
	s_addc_u32 s19, s29, 0
	s_add_u32 s20, s28, 0x16d00000
	s_addc_u32 s21, s29, 0
	s_add_u32 s22, s28, 0x18600000
	s_addc_u32 s23, s29, 0
	s_mov_b64 s[2:3], s[28:29]
	s_add_u32 s28, s2, 0x19700000
	s_addc_u32 s29, s3, 0
	s_add_u32 s0, s2, 0x18600080
	s_addc_u32 s1, s3, 0
	s_add_u32 s2, s2, 0x16d03000
	s_addc_u32 s3, s3, 0
	s_mov_b32 s30, s51
	s_branch .LBB0_745

; DEV void phase_attn(const Params& p, char* smem) {
;   for (int item = blockIdx.x; item < 512 + 16; item += gridDim.x) attn_item(p, item, smem);
; }
.LBB0_770:
	s_setprio 0
	v_mov_b32_e32 v196, 0x3ba10414
	v_mov_b32_e32 v197, 0x13c00
	v_mov_b32_e32 v198, 0x13c04
	v_mov_b32_e32 v199, 1
	v_mov_b32_e32 v200, 0x13b40
	v_mov_b32_e32 v201, 0x13b50
	v_mov_b32_e32 v202, 0x13b60
	v_mov_b32_e32 v203, 0x13b70
	v_mov_b32_e32 v204, 0x13b80
	v_mov_b32_e32 v205, 0x13b90
	v_mov_b32_e32 v206, 0x13ba0
	v_mov_b32_e32 v207, 0x13bb0
	v_mov_b32_e32 v208, 0x13bc0
	v_mov_b32_e32 v209, 0x13bd0
	v_mov_b32_e32 v210, 0x13be0
	v_mov_b32_e32 v211, 0x358637bd
	v_mov_b32_e32 v212, 0x8300000
	v_mov_b32_e32 v213, 0x7fc00000
	v_mov_b32_e32 v222, 0xb9c68948
	v_mov_b32_e32 v223, 0x7f800000
	v_mov_b32_e32 v224, 0xe300000
	v_mov_b32_e32 v225, 0x41b17218
	v_mov_b32_e32 v226, -12
	v_mov_b32_e32 v227, 0x9800
	v_mov_b32_e32 v228, 0x6700000
	v_mov_b32_e32 v229, 0xc300000
	v_xor_b32_e32 v220, 4, v216
	v_xor_b32_e32 v221, 8, v216
	v_not_b32_e32 v230, 63
	v_not_b32_e32 v231, 31
	v_readlane_b32 s30, v253, 11
	v_readlane_b32 s28, v254, 0
	v_readlane_b32 s31, v253, 12
	s_movk_i32 s19, 0x880
	s_movk_i32 s23, 0x3fff
	s_movk_i32 s21, 0x2000
	v_readlane_b32 s29, v254, 1
